# bf16 GEMM epilogue stores write-through (sc1): outputs do not displace operand tiles in L2
# speedup vs baseline: 1.0013x; 1.0013x over previous
; __device__ __forceinline__ float sigm(float x) { return 1.f / (1.f + __expf(-x)); }
;     __device__ __forceinline__ void operator()(const pg8::f32x4 (&acc)[2][2][4][2], const pg8::Unit& u, int wr, int wc, int fr, int fq) const {
;     ...
;                     for (int bj = 0; bj < 2; ++bj) {
;                         float o[8];
; #pragma unroll
;                         for (int n = 0; n < 2; ++n)
; #pragma unroll
;                             for (int j = 0; j < 4; ++j) o[4 * n + j] = acc[ai][bj][m][n][j] * rsv;
;                         if (sig) {
; #pragma unroll
;                             for (int e = 0; e < 8; ++e) o[e] = sigm(o[e]);
;                             if (mode == EM_Z2) { const f32x4 h0 = *(const f32x4*)(gain0 + colb - 2048 + bj * 128 + cl), h1_ = *(const f32x4*)(gain0 + colb - 2048 + bj * 128 + cl + 4);
; #pragma unroll
;                                 for (int e = 0; e < 4; ++e) { o[e] *= h0[e]; o[4 + e] *= h1_[e]; } }
;                         }
;                         if (gt) { float gv[8]; unpack8(*(const u32x4*)(gt + (size_t)row * Z2_LD + gcol + bj * 128 + cl), gv);
; #pragma unroll
;                             for (int e = 0; e < 8; ++e) o[e] *= gv[e]; }
.LBB0_360:
	v_mov_b32_e32 v177, v176
	v_cndmask_b32_e64 v0, 0, 1, s[50:51]
	v_pk_mul_f32 v[186:187], v[118:119], v[176:177]
	v_pk_mul_f32 v[190:191], v[120:121], v[176:177]
	v_pk_mul_f32 v[188:189], v[114:115], v[176:177]
	v_cmp_ne_u32_e64 s[48:49], 1, v0
	s_andn2_b64 vcc, exec, s[50:51]
	v_pk_mul_f32 v[192:193], v[116:117], v[176:177]
	global_store_dwordx4 v[184:185], v[130:133], off sc1
	s_cbranch_vccnz .LBB0_363
	v_mul_f32_e32 v0, 0xbfb8aa3b, v186
	v_exp_f32_e32 v130, v0
	v_mul_f32_e32 v0, 0xbfb8aa3b, v187
	v_exp_f32_e32 v131, v0
	s_nop 0
	v_pk_add_f32 v[130:131], v[130:131], 1.0 op_sel_hi:[1,0]
	s_nop 0
	s_nop 0
	v_rcp_f32_e32 v187, v131
	s_nop 0
	s_nop 0
	v_rcp_f32_e32 v186, v130
	s_nop 0
	v_mul_f32_e32 v0, 0xbfb8aa3b, v190
	v_exp_f32_e32 v130, v0
	v_mul_f32_e32 v0, 0xbfb8aa3b, v191
	v_exp_f32_e32 v131, v0
	s_nop 0
	v_pk_add_f32 v[130:131], v[130:131], 1.0 op_sel_hi:[1,0]
	s_nop 0
	s_nop 0
	v_rcp_f32_e32 v191, v131
	s_nop 0
	s_nop 0
	v_rcp_f32_e32 v190, v130
	s_nop 0
	v_mul_f32_e32 v0, 0xbfb8aa3b, v188
	v_exp_f32_e32 v130, v0
	v_mul_f32_e32 v0, 0xbfb8aa3b, v189
	v_exp_f32_e32 v131, v0
	s_nop 0
	v_pk_add_f32 v[130:131], v[130:131], 1.0 op_sel_hi:[1,0]
	s_nop 0
	s_nop 0
	v_rcp_f32_e32 v189, v131
	s_nop 0
	s_nop 0
	v_rcp_f32_e32 v188, v130
	s_nop 0
	v_mul_f32_e32 v0, 0xbfb8aa3b, v192
	v_exp_f32_e32 v130, v0
	v_mul_f32_e32 v0, 0xbfb8aa3b, v193
	v_exp_f32_e32 v131, v0
	s_nop 0
	v_pk_add_f32 v[130:131], v[130:131], 1.0 op_sel_hi:[1,0]
	s_nop 0
	s_nop 0
	v_rcp_f32_e32 v193, v131
	s_nop 0
	s_nop 0
	v_rcp_f32_e32 v192, v130
	s_nop 0
	s_and_b64 vcc, exec, s[44:45]
	s_cbranch_vccnz .LBB0_363
	global_load_dwordx4 v[130:133], v[134:135], off offset:512
	global_load_dwordx4 v[230:233], v[134:135], off offset:528
	s_waitcnt vmcnt(1)
	v_pk_mul_f32 v[190:191], v[190:191], v[132:133]
	v_pk_mul_f32 v[186:187], v[186:187], v[130:131]
	s_waitcnt vmcnt(0)
	v_pk_mul_f32 v[192:193], v[192:193], v[232:233]
	v_pk_mul_f32 v[188:189], v[188:189], v[230:231]

; __device__ __forceinline__ u32x4 pack8(const float (&f)[8]) { u32x4 w; w.x = pk2(f[0], f[1]); w.y = pk2(f[2], f[3]); w.z = pk2(f[4], f[5]); w.w = pk2(f[6], f[7]); return w; }
;     __device__ __forceinline__ void operator()(const pg8::f32x4 (&acc)[2][2][4][2], const pg8::Unit& u, int wr, int wc, int fr, int fq) const {
;     ...
;                         bf16_t* p = dst + (size_t)row * ldc + colb + bj * 128 + cl;
;                         if (addt) { float tv[8]; unpack8(*(const u32x4*)p, tv);
; #pragma unroll
;                             for (int e = 0; e < 8; ++e) o[e] += tv[e]; }
;                         if (ssq) {
; #pragma unroll
;                             for (int e = 0; e < 8; ++e) sacc += o[e] * o[e]; }
;                         if (mode == EM_UP) __builtin_nontemporal_store(pack8(o), (u32x4*)p); else *(u32x4*)p = pack8(o);
;                     }
;                     if (ssq) { sacc += __shfl_xor(sacc, 16); sacc += __shfl_xor(sacc, 32); if (fq == 0) atomicAdd(ssq + row, sacc); }
.LBB0_374:
	global_store_dwordx4 v[184:185], v[130:133], off offset:256 sc1
	s_andn2_b64 vcc, exec, s[72:73]
	s_nop 0
	v_cndmask_b32_e64 v130, 0, 1, s[72:73]
	v_cmp_ne_u32_e64 s[54:55], 1, v130
	s_cbranch_vccnz .LBB0_378
	v_and_b32_e32 v131, 64, v220
	v_xor_b32_e32 v130, 16, v220
	v_add_u32_e32 v131, 64, v131
	v_cmp_lt_i32_e32 vcc, v130, v131
	s_nop 1
	v_cndmask_b32_e32 v130, v220, v130, vcc
	v_lshlrev_b32_e32 v130, 2, v130
	ds_bpermute_b32 v130, v130, v0
	s_waitcnt lgkmcnt(0)
	v_add_f32_e32 v0, v0, v130
	v_xor_b32_e32 v130, 32, v220
	v_cmp_lt_i32_e32 vcc, v130, v131
	s_nop 1
	v_cndmask_b32_e32 v130, v220, v130, vcc
	v_lshlrev_b32_e32 v130, 2, v130
	ds_bpermute_b32 v130, v130, v0
	s_and_saveexec_b64 s[18:19], s[40:41]
	s_cbranch_execz .LBB0_377
	v_lshl_add_u64 v[132:133], v[178:179], 2, s[60:61]
	s_waitcnt lgkmcnt(0)
	v_add_f32_e32 v0, v0, v130
	global_atomic_add_f32 v[132:133], v0, off

; __device__ __forceinline__ float sigm(float x) { return 1.f / (1.f + __expf(-x)); }
;     __device__ __forceinline__ void operator()(const pg8::f32x4 (&acc)[2][2][4][2], const pg8::Unit& u, int wr, int wc, int fr, int fq) const {
;     ...
;                     for (int bj = 0; bj < 2; ++bj) {
;                         float o[8];
; #pragma unroll
;                         for (int n = 0; n < 2; ++n)
; #pragma unroll
;                             for (int j = 0; j < 4; ++j) o[4 * n + j] = acc[ai][bj][m][n][j] * rsv;
;                         if (sig) {
; #pragma unroll
;                             for (int e = 0; e < 8; ++e) o[e] = sigm(o[e]);
;                             if (mode == EM_Z2) { const f32x4 h0 = *(const f32x4*)(gain0 + colb - 2048 + bj * 128 + cl), h1_ = *(const f32x4*)(gain0 + colb - 2048 + bj * 128 + cl + 4);
; #pragma unroll
;                                 for (int e = 0; e < 4; ++e) { o[e] *= h0[e]; o[4 + e] *= h1_[e]; } }
;                         }
;                         if (gt) { float gv[8]; unpack8(*(const u32x4*)(gt + (size_t)row * Z2_LD + gcol + bj * 128 + cl), gv);
; #pragma unroll
;                             for (int e = 0; e < 8; ++e) o[e] *= gv[e]; }
.LBB0_387:
	v_mov_b32_e32 v175, v174
	v_pk_mul_f32 v[186:187], v[102:103], v[174:175]
	v_pk_mul_f32 v[190:191], v[104:105], v[174:175]
	v_pk_mul_f32 v[188:189], v[98:99], v[174:175]
	s_and_b64 vcc, exec, s[48:49]
	v_pk_mul_f32 v[192:193], v[100:101], v[174:175]
	global_store_dwordx4 v[184:185], v[130:133], off sc1
	s_cbranch_vccnz .LBB0_390
	v_mul_f32_e32 v0, 0xbfb8aa3b, v186
	v_exp_f32_e32 v130, v0
	v_mul_f32_e32 v0, 0xbfb8aa3b, v187
	v_exp_f32_e32 v131, v0
	s_nop 0
	v_pk_add_f32 v[130:131], v[130:131], 1.0 op_sel_hi:[1,0]
	s_nop 0
	s_nop 0
	v_rcp_f32_e32 v187, v131
	s_nop 0
	s_nop 0
	v_rcp_f32_e32 v186, v130
	s_nop 0
	v_mul_f32_e32 v0, 0xbfb8aa3b, v190
	v_exp_f32_e32 v130, v0
	v_mul_f32_e32 v0, 0xbfb8aa3b, v191
	v_exp_f32_e32 v131, v0
	s_nop 0
	v_pk_add_f32 v[130:131], v[130:131], 1.0 op_sel_hi:[1,0]
	s_nop 0
	s_nop 0
	v_rcp_f32_e32 v191, v131
	s_nop 0
	s_nop 0
	v_rcp_f32_e32 v190, v130
	s_nop 0
	v_mul_f32_e32 v0, 0xbfb8aa3b, v188
	v_exp_f32_e32 v130, v0
	v_mul_f32_e32 v0, 0xbfb8aa3b, v189
	v_exp_f32_e32 v131, v0
	s_nop 0
	v_pk_add_f32 v[130:131], v[130:131], 1.0 op_sel_hi:[1,0]
	s_nop 0
	s_nop 0
	v_rcp_f32_e32 v189, v131
	s_nop 0
	s_nop 0
	v_rcp_f32_e32 v188, v130
	s_nop 0
	v_mul_f32_e32 v0, 0xbfb8aa3b, v192
	v_exp_f32_e32 v130, v0
	v_mul_f32_e32 v0, 0xbfb8aa3b, v193
	v_exp_f32_e32 v131, v0
	s_nop 0
	v_pk_add_f32 v[130:131], v[130:131], 1.0 op_sel_hi:[1,0]
	s_nop 0
	s_nop 0
	v_rcp_f32_e32 v193, v131
	s_nop 0
	s_nop 0
	v_rcp_f32_e32 v192, v130
	s_nop 0
	s_and_b64 vcc, exec, s[44:45]
	s_cbranch_vccnz .LBB0_390
	global_load_dwordx4 v[130:133], v[134:135], off offset:512
	global_load_dwordx4 v[230:233], v[134:135], off offset:528
	s_waitcnt vmcnt(1)
	v_pk_mul_f32 v[190:191], v[190:191], v[132:133]
	v_pk_mul_f32 v[186:187], v[186:187], v[130:131]
	s_waitcnt vmcnt(0)
	v_pk_mul_f32 v[192:193], v[192:193], v[232:233]
	v_pk_mul_f32 v[188:189], v[188:189], v[230:231]

; __device__ __forceinline__ u32x4 pack8(const float (&f)[8]) { u32x4 w; w.x = pk2(f[0], f[1]); w.y = pk2(f[2], f[3]); w.z = pk2(f[4], f[5]); w.w = pk2(f[6], f[7]); return w; }
;     __device__ __forceinline__ void operator()(const pg8::f32x4 (&acc)[2][2][4][2], const pg8::Unit& u, int wr, int wc, int fr, int fq) const {
;     ...
;                         bf16_t* p = dst + (size_t)row * ldc + colb + bj * 128 + cl;
;                         if (addt) { float tv[8]; unpack8(*(const u32x4*)p, tv);
; #pragma unroll
;                             for (int e = 0; e < 8; ++e) o[e] += tv[e]; }
;                         if (ssq) {
; #pragma unroll
;                             for (int e = 0; e < 8; ++e) sacc += o[e] * o[e]; }
;                         if (mode == EM_UP) __builtin_nontemporal_store(pack8(o), (u32x4*)p); else *(u32x4*)p = pack8(o);
.LBB0_399:
	s_and_b64 vcc, exec, s[54:55]
	global_store_dwordx4 v[184:185], v[130:133], off offset:256 sc1
	s_cbranch_vccz .LBB0_406
	s_branch .LBB0_409

; __device__ __forceinline__ u32x4 pack8(const float (&f)[8]) { u32x4 w; w.x = pk2(f[0], f[1]); w.y = pk2(f[2], f[3]); w.z = pk2(f[4], f[5]); w.w = pk2(f[6], f[7]); return w; }
;     __device__ __forceinline__ void operator()(const pg8::f32x4 (&acc)[2][2][4][2], const pg8::Unit& u, int wr, int wc, int fr, int fq) const {
;     ...
;                         bf16_t* p = dst + (size_t)row * ldc + colb + bj * 128 + cl;
;                         if (addt) { float tv[8]; unpack8(*(const u32x4*)p, tv);
; #pragma unroll
;                             for (int e = 0; e < 8; ++e) o[e] += tv[e]; }
;                         if (ssq) {
; #pragma unroll
;                             for (int e = 0; e < 8; ++e) sacc += o[e] * o[e]; }
;                         if (mode == EM_UP) __builtin_nontemporal_store(pack8(o), (u32x4*)p); else *(u32x4*)p = pack8(o);
.LBB0_405:
	v_cvt_pk_bf16_f32 v130, v186, v187
	v_cvt_pk_bf16_f32 v131, v190, v191
	v_cvt_pk_bf16_f32 v132, v188, v189
	v_cvt_pk_bf16_f32 v133, v192, v193
	s_and_b64 vcc, exec, s[54:55]
	global_store_dwordx4 v[184:185], v[130:133], off offset:256 sc1
	s_cbranch_vccnz .LBB0_409

; __device__ __forceinline__ float sigm(float x) { return 1.f / (1.f + __expf(-x)); }
;     __device__ __forceinline__ void operator()(const pg8::f32x4 (&acc)[2][2][4][2], const pg8::Unit& u, int wr, int wc, int fr, int fq) const {
;     ...
;                     for (int bj = 0; bj < 2; ++bj) {
;                         float o[8];
; #pragma unroll
;                         for (int n = 0; n < 2; ++n)
; #pragma unroll
;                             for (int j = 0; j < 4; ++j) o[4 * n + j] = acc[ai][bj][m][n][j] * rsv;
;                         if (sig) {
; #pragma unroll
;                             for (int e = 0; e < 8; ++e) o[e] = sigm(o[e]);
;                             if (mode == EM_Z2) { const f32x4 h0 = *(const f32x4*)(gain0 + colb - 2048 + bj * 128 + cl), h1_ = *(const f32x4*)(gain0 + colb - 2048 + bj * 128 + cl + 4);
; #pragma unroll
;                                 for (int e = 0; e < 4; ++e) { o[e] *= h0[e]; o[4 + e] *= h1_[e]; } }
;                         }
;                         if (gt) { float gv[8]; unpack8(*(const u32x4*)(gt + (size_t)row * Z2_LD + gcol + bj * 128 + cl), gv);
; #pragma unroll
;                             for (int e = 0; e < 8; ++e) o[e] *= gv[e]; }
.LBB0_418:
	v_mov_b32_e32 v173, v172
	v_pk_mul_f32 v[186:187], v[86:87], v[172:173]
	v_pk_mul_f32 v[190:191], v[88:89], v[172:173]
	v_pk_mul_f32 v[188:189], v[82:83], v[172:173]
	s_and_b64 vcc, exec, s[48:49]
	v_pk_mul_f32 v[192:193], v[84:85], v[172:173]
	global_store_dwordx4 v[184:185], v[130:133], off sc1
	s_cbranch_vccnz .LBB0_421
	v_mul_f32_e32 v0, 0xbfb8aa3b, v186
	v_exp_f32_e32 v130, v0
	v_mul_f32_e32 v0, 0xbfb8aa3b, v187
	v_exp_f32_e32 v131, v0
	s_nop 0
	v_pk_add_f32 v[130:131], v[130:131], 1.0 op_sel_hi:[1,0]
	s_nop 0
	s_nop 0
	v_rcp_f32_e32 v187, v131
	s_nop 0
	s_nop 0
	v_rcp_f32_e32 v186, v130
	s_nop 0
	v_mul_f32_e32 v0, 0xbfb8aa3b, v190
	v_exp_f32_e32 v130, v0
	v_mul_f32_e32 v0, 0xbfb8aa3b, v191
	v_exp_f32_e32 v131, v0
	s_nop 0
	v_pk_add_f32 v[130:131], v[130:131], 1.0 op_sel_hi:[1,0]
	s_nop 0
	s_nop 0
	v_rcp_f32_e32 v191, v131
	s_nop 0
	s_nop 0
	v_rcp_f32_e32 v190, v130
	s_nop 0
	v_mul_f32_e32 v0, 0xbfb8aa3b, v188
	v_exp_f32_e32 v130, v0
	v_mul_f32_e32 v0, 0xbfb8aa3b, v189
	v_exp_f32_e32 v131, v0
	s_nop 0
	v_pk_add_f32 v[130:131], v[130:131], 1.0 op_sel_hi:[1,0]
	s_nop 0
	s_nop 0
	v_rcp_f32_e32 v189, v131
	s_nop 0
	s_nop 0
	v_rcp_f32_e32 v188, v130
	s_nop 0
	v_mul_f32_e32 v0, 0xbfb8aa3b, v192
	v_exp_f32_e32 v130, v0
	v_mul_f32_e32 v0, 0xbfb8aa3b, v193
	v_exp_f32_e32 v131, v0
	s_nop 0
	v_pk_add_f32 v[130:131], v[130:131], 1.0 op_sel_hi:[1,0]
	s_nop 0
	s_nop 0
	v_rcp_f32_e32 v193, v131
	s_nop 0
	s_nop 0
	v_rcp_f32_e32 v192, v130
	s_nop 0
	s_and_b64 vcc, exec, s[44:45]
	s_cbranch_vccnz .LBB0_421
	global_load_dwordx4 v[130:133], v[134:135], off offset:512
	global_load_dwordx4 v[230:233], v[134:135], off offset:528
	s_waitcnt vmcnt(1)
	v_pk_mul_f32 v[190:191], v[190:191], v[132:133]
	v_pk_mul_f32 v[186:187], v[186:187], v[130:131]
	s_waitcnt vmcnt(0)
	v_pk_mul_f32 v[192:193], v[192:193], v[232:233]
	v_pk_mul_f32 v[188:189], v[188:189], v[230:231]

; __device__ __forceinline__ float sigm(float x) { return 1.f / (1.f + __expf(-x)); }
;     __device__ __forceinline__ void operator()(const pg8::f32x4 (&acc)[2][2][4][2], const pg8::Unit& u, int wr, int wc, int fr, int fq) const {
;     ...
;                     for (int bj = 0; bj < 2; ++bj) {
;                         float o[8];
; #pragma unroll
;                         for (int n = 0; n < 2; ++n)
; #pragma unroll
;                             for (int j = 0; j < 4; ++j) o[4 * n + j] = acc[ai][bj][m][n][j] * rsv;
;                         if (sig) {
; #pragma unroll
;                             for (int e = 0; e < 8; ++e) o[e] = sigm(o[e]);
;                             if (mode == EM_Z2) { const f32x4 h0 = *(const f32x4*)(gain0 + colb - 2048 + bj * 128 + cl), h1_ = *(const f32x4*)(gain0 + colb - 2048 + bj * 128 + cl + 4);
; #pragma unroll
;                                 for (int e = 0; e < 4; ++e) { o[e] *= h0[e]; o[4 + e] *= h1_[e]; } }
;                         }
;                         if (gt) { float gv[8]; unpack8(*(const u32x4*)(gt + (size_t)row * Z2_LD + gcol + bj * 128 + cl), gv);
; #pragma unroll
;                             for (int e = 0; e < 8; ++e) o[e] *= gv[e]; }
.LBB0_447:
	v_mov_b32_e32 v171, v170
	v_pk_mul_f32 v[186:187], v[70:71], v[170:171]
	v_pk_mul_f32 v[190:191], v[72:73], v[170:171]
	v_pk_mul_f32 v[188:189], v[66:67], v[170:171]
	s_and_b64 vcc, exec, s[48:49]
	v_pk_mul_f32 v[192:193], v[68:69], v[170:171]
	global_store_dwordx4 v[184:185], v[130:133], off sc1
	s_cbranch_vccnz .LBB0_450
	v_mul_f32_e32 v0, 0xbfb8aa3b, v186
	v_exp_f32_e32 v130, v0
	v_mul_f32_e32 v0, 0xbfb8aa3b, v187
	v_exp_f32_e32 v131, v0
	s_nop 0
	v_pk_add_f32 v[130:131], v[130:131], 1.0 op_sel_hi:[1,0]
	s_nop 0
	s_nop 0
	v_rcp_f32_e32 v187, v131
	s_nop 0
	s_nop 0
	v_rcp_f32_e32 v186, v130
	s_nop 0
	v_mul_f32_e32 v0, 0xbfb8aa3b, v190
	v_exp_f32_e32 v130, v0
	v_mul_f32_e32 v0, 0xbfb8aa3b, v191
	v_exp_f32_e32 v131, v0
	s_nop 0
	v_pk_add_f32 v[130:131], v[130:131], 1.0 op_sel_hi:[1,0]
	s_nop 0
	s_nop 0
	v_rcp_f32_e32 v191, v131
	s_nop 0
	s_nop 0
	v_rcp_f32_e32 v190, v130
	s_nop 0
	v_mul_f32_e32 v0, 0xbfb8aa3b, v188
	v_exp_f32_e32 v130, v0
	v_mul_f32_e32 v0, 0xbfb8aa3b, v189
	v_exp_f32_e32 v131, v0
	s_nop 0
	v_pk_add_f32 v[130:131], v[130:131], 1.0 op_sel_hi:[1,0]
	s_nop 0
	s_nop 0
	v_rcp_f32_e32 v189, v131
	s_nop 0
	s_nop 0
	v_rcp_f32_e32 v188, v130
	s_nop 0
	v_mul_f32_e32 v0, 0xbfb8aa3b, v192
	v_exp_f32_e32 v130, v0
	v_mul_f32_e32 v0, 0xbfb8aa3b, v193
	v_exp_f32_e32 v131, v0
	s_nop 0
	v_pk_add_f32 v[130:131], v[130:131], 1.0 op_sel_hi:[1,0]
	s_nop 0
	s_nop 0
	v_rcp_f32_e32 v193, v131
	s_nop 0
	s_nop 0
	v_rcp_f32_e32 v192, v130
	s_nop 0
	s_and_b64 vcc, exec, s[44:45]
	s_cbranch_vccnz .LBB0_450
	global_load_dwordx4 v[130:133], v[134:135], off offset:512
	global_load_dwordx4 v[230:233], v[134:135], off offset:528
	s_waitcnt vmcnt(1)
	v_pk_mul_f32 v[190:191], v[190:191], v[132:133]
	v_pk_mul_f32 v[186:187], v[186:187], v[130:131]
	s_waitcnt vmcnt(0)
	v_pk_mul_f32 v[192:193], v[192:193], v[232:233]
	v_pk_mul_f32 v[188:189], v[188:189], v[230:231]

; __device__ __forceinline__ float sigm(float x) { return 1.f / (1.f + __expf(-x)); }
;     __device__ __forceinline__ void operator()(const pg8::f32x4 (&acc)[2][2][4][2], const pg8::Unit& u, int wr, int wc, int fr, int fq) const {
;     ...
;                     for (int bj = 0; bj < 2; ++bj) {
;                         float o[8];
; #pragma unroll
;                         for (int n = 0; n < 2; ++n)
; #pragma unroll
;                             for (int j = 0; j < 4; ++j) o[4 * n + j] = acc[ai][bj][m][n][j] * rsv;
;                         if (sig) {
; #pragma unroll
;                             for (int e = 0; e < 8; ++e) o[e] = sigm(o[e]);
;                             if (mode == EM_Z2) { const f32x4 h0 = *(const f32x4*)(gain0 + colb - 2048 + bj * 128 + cl), h1_ = *(const f32x4*)(gain0 + colb - 2048 + bj * 128 + cl + 4);
; #pragma unroll
;                                 for (int e = 0; e < 4; ++e) { o[e] *= h0[e]; o[4 + e] *= h1_[e]; } }
;                         }
;                         if (gt) { float gv[8]; unpack8(*(const u32x4*)(gt + (size_t)row * Z2_LD + gcol + bj * 128 + cl), gv);
; #pragma unroll
;                             for (int e = 0; e < 8; ++e) o[e] *= gv[e]; }
.LBB0_476:
	v_mov_b32_e32 v169, v168
	v_pk_mul_f32 v[186:187], v[54:55], v[168:169]
	v_pk_mul_f32 v[190:191], v[56:57], v[168:169]
	v_pk_mul_f32 v[188:189], v[50:51], v[168:169]
	s_and_b64 vcc, exec, s[48:49]
	v_pk_mul_f32 v[192:193], v[52:53], v[168:169]
	global_store_dwordx4 v[184:185], v[130:133], off sc1
	s_cbranch_vccnz .LBB0_479
	v_mul_f32_e32 v0, 0xbfb8aa3b, v186
	v_exp_f32_e32 v130, v0
	v_mul_f32_e32 v0, 0xbfb8aa3b, v187
	v_exp_f32_e32 v131, v0
	s_nop 0
	v_pk_add_f32 v[130:131], v[130:131], 1.0 op_sel_hi:[1,0]
	s_nop 0
	s_nop 0
	v_rcp_f32_e32 v187, v131
	s_nop 0
	s_nop 0
	v_rcp_f32_e32 v186, v130
	s_nop 0
	v_mul_f32_e32 v0, 0xbfb8aa3b, v190
	v_exp_f32_e32 v130, v0
	v_mul_f32_e32 v0, 0xbfb8aa3b, v191
	v_exp_f32_e32 v131, v0
	s_nop 0
	v_pk_add_f32 v[130:131], v[130:131], 1.0 op_sel_hi:[1,0]
	s_nop 0
	s_nop 0
	v_rcp_f32_e32 v191, v131
	s_nop 0
	s_nop 0
	v_rcp_f32_e32 v190, v130
	s_nop 0
	v_mul_f32_e32 v0, 0xbfb8aa3b, v188
	v_exp_f32_e32 v130, v0
	v_mul_f32_e32 v0, 0xbfb8aa3b, v189
	v_exp_f32_e32 v131, v0
	s_nop 0
	v_pk_add_f32 v[130:131], v[130:131], 1.0 op_sel_hi:[1,0]
	s_nop 0
	s_nop 0
	v_rcp_f32_e32 v189, v131
	s_nop 0
	s_nop 0
	v_rcp_f32_e32 v188, v130
	s_nop 0
	v_mul_f32_e32 v0, 0xbfb8aa3b, v192
	v_exp_f32_e32 v130, v0
	v_mul_f32_e32 v0, 0xbfb8aa3b, v193
	v_exp_f32_e32 v131, v0
	s_nop 0
	v_pk_add_f32 v[130:131], v[130:131], 1.0 op_sel_hi:[1,0]
	s_nop 0
	s_nop 0
	v_rcp_f32_e32 v193, v131
	s_nop 0
	s_nop 0
	v_rcp_f32_e32 v192, v130
	s_nop 0
	s_and_b64 vcc, exec, s[44:45]
	s_cbranch_vccnz .LBB0_479
	global_load_dwordx4 v[130:133], v[134:135], off offset:512
	global_load_dwordx4 v[230:233], v[134:135], off offset:528
	s_waitcnt vmcnt(1)
	v_pk_mul_f32 v[190:191], v[190:191], v[132:133]
	v_pk_mul_f32 v[186:187], v[186:187], v[130:131]
	s_waitcnt vmcnt(0)
	v_pk_mul_f32 v[192:193], v[192:193], v[232:233]
	v_pk_mul_f32 v[188:189], v[188:189], v[230:231]

; __device__ __forceinline__ float sigm(float x) { return 1.f / (1.f + __expf(-x)); }
;     __device__ __forceinline__ void operator()(const pg8::f32x4 (&acc)[2][2][4][2], const pg8::Unit& u, int wr, int wc, int fr, int fq) const {
;     ...
;                     for (int bj = 0; bj < 2; ++bj) {
;                         float o[8];
; #pragma unroll
;                         for (int n = 0; n < 2; ++n)
; #pragma unroll
;                             for (int j = 0; j < 4; ++j) o[4 * n + j] = acc[ai][bj][m][n][j] * rsv;
;                         if (sig) {
; #pragma unroll
;                             for (int e = 0; e < 8; ++e) o[e] = sigm(o[e]);
;                             if (mode == EM_Z2) { const f32x4 h0 = *(const f32x4*)(gain0 + colb - 2048 + bj * 128 + cl), h1_ = *(const f32x4*)(gain0 + colb - 2048 + bj * 128 + cl + 4);
; #pragma unroll
;                                 for (int e = 0; e < 4; ++e) { o[e] *= h0[e]; o[4 + e] *= h1_[e]; } }
;                         }
;                         if (gt) { float gv[8]; unpack8(*(const u32x4*)(gt + (size_t)row * Z2_LD + gcol + bj * 128 + cl), gv);
; #pragma unroll
;                             for (int e = 0; e < 8; ++e) o[e] *= gv[e]; }
.LBB0_505:
	v_mov_b32_e32 v167, v166
	v_pk_mul_f32 v[186:187], v[38:39], v[166:167]
	v_pk_mul_f32 v[190:191], v[40:41], v[166:167]
	v_pk_mul_f32 v[188:189], v[34:35], v[166:167]
	s_and_b64 vcc, exec, s[48:49]
	v_pk_mul_f32 v[192:193], v[36:37], v[166:167]
	global_store_dwordx4 v[184:185], v[130:133], off sc1
	s_cbranch_vccnz .LBB0_508
	v_mul_f32_e32 v0, 0xbfb8aa3b, v186
	v_exp_f32_e32 v130, v0
	v_mul_f32_e32 v0, 0xbfb8aa3b, v187
	v_exp_f32_e32 v131, v0
	s_nop 0
	v_pk_add_f32 v[130:131], v[130:131], 1.0 op_sel_hi:[1,0]
	s_nop 0
	s_nop 0
	v_rcp_f32_e32 v187, v131
	s_nop 0
	s_nop 0
	v_rcp_f32_e32 v186, v130
	s_nop 0
	v_mul_f32_e32 v0, 0xbfb8aa3b, v190
	v_exp_f32_e32 v130, v0
	v_mul_f32_e32 v0, 0xbfb8aa3b, v191
	v_exp_f32_e32 v131, v0
	s_nop 0
	v_pk_add_f32 v[130:131], v[130:131], 1.0 op_sel_hi:[1,0]
	s_nop 0
	s_nop 0
	v_rcp_f32_e32 v191, v131
	s_nop 0
	s_nop 0
	v_rcp_f32_e32 v190, v130
	s_nop 0
	v_mul_f32_e32 v0, 0xbfb8aa3b, v188
	v_exp_f32_e32 v130, v0
	v_mul_f32_e32 v0, 0xbfb8aa3b, v189
	v_exp_f32_e32 v131, v0
	s_nop 0
	v_pk_add_f32 v[130:131], v[130:131], 1.0 op_sel_hi:[1,0]
	s_nop 0
	s_nop 0
	v_rcp_f32_e32 v189, v131
	s_nop 0
	s_nop 0
	v_rcp_f32_e32 v188, v130
	s_nop 0
	v_mul_f32_e32 v0, 0xbfb8aa3b, v192
	v_exp_f32_e32 v130, v0
	v_mul_f32_e32 v0, 0xbfb8aa3b, v193
	v_exp_f32_e32 v131, v0
	s_nop 0
	v_pk_add_f32 v[130:131], v[130:131], 1.0 op_sel_hi:[1,0]
	s_nop 0
	s_nop 0
	v_rcp_f32_e32 v193, v131
	s_nop 0
	s_nop 0
	v_rcp_f32_e32 v192, v130
	s_nop 0
	s_and_b64 vcc, exec, s[44:45]
	s_cbranch_vccnz .LBB0_508
	global_load_dwordx4 v[130:133], v[134:135], off offset:512
	global_load_dwordx4 v[230:233], v[134:135], off offset:528
	s_waitcnt vmcnt(1)
	v_pk_mul_f32 v[190:191], v[190:191], v[132:133]
	v_pk_mul_f32 v[186:187], v[186:187], v[130:131]
	s_waitcnt vmcnt(0)
	v_pk_mul_f32 v[192:193], v[192:193], v[232:233]
	v_pk_mul_f32 v[188:189], v[188:189], v[230:231]

; __device__ __forceinline__ float sigm(float x) { return 1.f / (1.f + __expf(-x)); }
;     __device__ __forceinline__ void operator()(const pg8::f32x4 (&acc)[2][2][4][2], const pg8::Unit& u, int wr, int wc, int fr, int fq) const {
;     ...
;                     for (int bj = 0; bj < 2; ++bj) {
;                         float o[8];
; #pragma unroll
;                         for (int n = 0; n < 2; ++n)
; #pragma unroll
;                             for (int j = 0; j < 4; ++j) o[4 * n + j] = acc[ai][bj][m][n][j] * rsv;
;                         if (sig) {
; #pragma unroll
;                             for (int e = 0; e < 8; ++e) o[e] = sigm(o[e]);
;                             if (mode == EM_Z2) { const f32x4 h0 = *(const f32x4*)(gain0 + colb - 2048 + bj * 128 + cl), h1_ = *(const f32x4*)(gain0 + colb - 2048 + bj * 128 + cl + 4);
; #pragma unroll
;                                 for (int e = 0; e < 4; ++e) { o[e] *= h0[e]; o[4 + e] *= h1_[e]; } }
;                         }
;                         if (gt) { float gv[8]; unpack8(*(const u32x4*)(gt + (size_t)row * Z2_LD + gcol + bj * 128 + cl), gv);
; #pragma unroll
;                             for (int e = 0; e < 8; ++e) o[e] *= gv[e]; }
.LBB0_534:
	v_mov_b32_e32 v165, v164
	v_pk_mul_f32 v[186:187], v[22:23], v[164:165]
	v_pk_mul_f32 v[190:191], v[24:25], v[164:165]
	v_pk_mul_f32 v[188:189], v[18:19], v[164:165]
	s_and_b64 vcc, exec, s[48:49]
	v_pk_mul_f32 v[192:193], v[20:21], v[164:165]
	global_store_dwordx4 v[184:185], v[130:133], off sc1
	s_cbranch_vccnz .LBB0_537
	v_mul_f32_e32 v0, 0xbfb8aa3b, v186
	v_exp_f32_e32 v130, v0
	v_mul_f32_e32 v0, 0xbfb8aa3b, v187
	v_exp_f32_e32 v131, v0
	s_nop 0
	v_pk_add_f32 v[130:131], v[130:131], 1.0 op_sel_hi:[1,0]
	s_nop 0
	s_nop 0
	v_rcp_f32_e32 v187, v131
	s_nop 0
	s_nop 0
	v_rcp_f32_e32 v186, v130
	s_nop 0
	v_mul_f32_e32 v0, 0xbfb8aa3b, v190
	v_exp_f32_e32 v130, v0
	v_mul_f32_e32 v0, 0xbfb8aa3b, v191
	v_exp_f32_e32 v131, v0
	s_nop 0
	v_pk_add_f32 v[130:131], v[130:131], 1.0 op_sel_hi:[1,0]
	s_nop 0
	s_nop 0
	v_rcp_f32_e32 v191, v131
	s_nop 0
	s_nop 0
	v_rcp_f32_e32 v190, v130
	s_nop 0
	v_mul_f32_e32 v0, 0xbfb8aa3b, v188
	v_exp_f32_e32 v130, v0
	v_mul_f32_e32 v0, 0xbfb8aa3b, v189
	v_exp_f32_e32 v131, v0
	s_nop 0
	v_pk_add_f32 v[130:131], v[130:131], 1.0 op_sel_hi:[1,0]
	s_nop 0
	s_nop 0
	v_rcp_f32_e32 v189, v131
	s_nop 0
	s_nop 0
	v_rcp_f32_e32 v188, v130
	s_nop 0
	v_mul_f32_e32 v0, 0xbfb8aa3b, v192
	v_exp_f32_e32 v130, v0
	v_mul_f32_e32 v0, 0xbfb8aa3b, v193
	v_exp_f32_e32 v131, v0
	s_nop 0
	v_pk_add_f32 v[130:131], v[130:131], 1.0 op_sel_hi:[1,0]
	s_nop 0
	s_nop 0
	v_rcp_f32_e32 v193, v131
	s_nop 0
	s_nop 0
	v_rcp_f32_e32 v192, v130
	s_nop 0
	s_and_b64 vcc, exec, s[44:45]
	s_cbranch_vccnz .LBB0_537
	global_load_dwordx4 v[130:133], v[134:135], off offset:512
	global_load_dwordx4 v[230:233], v[134:135], off offset:528
	s_waitcnt vmcnt(1)
	v_pk_mul_f32 v[190:191], v[190:191], v[132:133]
	v_pk_mul_f32 v[186:187], v[186:187], v[130:131]
	s_waitcnt vmcnt(0)
	v_pk_mul_f32 v[192:193], v[192:193], v[232:233]
	v_pk_mul_f32 v[188:189], v[188:189], v[230:231]

; __device__ __forceinline__ float sigm(float x) { return 1.f / (1.f + __expf(-x)); }
;     __device__ __forceinline__ void operator()(const pg8::f32x4 (&acc)[2][2][4][2], const pg8::Unit& u, int wr, int wc, int fr, int fq) const {
;     ...
;                     for (int bj = 0; bj < 2; ++bj) {
;                         float o[8];
; #pragma unroll
;                         for (int n = 0; n < 2; ++n)
; #pragma unroll
;                             for (int j = 0; j < 4; ++j) o[4 * n + j] = acc[ai][bj][m][n][j] * rsv;
;                         if (sig) {
; #pragma unroll
;                             for (int e = 0; e < 8; ++e) o[e] = sigm(o[e]);
;                             if (mode == EM_Z2) { const f32x4 h0 = *(const f32x4*)(gain0 + colb - 2048 + bj * 128 + cl), h1_ = *(const f32x4*)(gain0 + colb - 2048 + bj * 128 + cl + 4);
; #pragma unroll
;                                 for (int e = 0; e < 4; ++e) { o[e] *= h0[e]; o[4 + e] *= h1_[e]; } }
;                         }
;                         if (gt) { float gv[8]; unpack8(*(const u32x4*)(gt + (size_t)row * Z2_LD + gcol + bj * 128 + cl), gv);
; #pragma unroll
;                             for (int e = 0; e < 8; ++e) o[e] *= gv[e]; }
.LBB0_563:
	v_mov_b32_e32 v163, v162
	v_pk_mul_f32 v[138:139], v[6:7], v[162:163]
	v_pk_mul_f32 v[186:187], v[8:9], v[162:163]
	v_pk_mul_f32 v[184:185], v[2:3], v[162:163]
	s_and_b64 vcc, exec, s[48:49]
	v_pk_mul_f32 v[188:189], v[4:5], v[162:163]
	global_store_dwordx4 v[136:137], v[130:133], off sc1
	s_cbranch_vccnz .LBB0_566
	v_mul_f32_e32 v0, 0xbfb8aa3b, v138
	v_exp_f32_e32 v130, v0
	v_mul_f32_e32 v0, 0xbfb8aa3b, v139
	v_exp_f32_e32 v131, v0
	s_nop 0
	v_pk_add_f32 v[130:131], v[130:131], 1.0 op_sel_hi:[1,0]
	s_nop 0
	s_nop 0
	v_rcp_f32_e32 v139, v131
	s_nop 0
	s_nop 0
	v_rcp_f32_e32 v138, v130
	s_nop 0
	v_mul_f32_e32 v0, 0xbfb8aa3b, v186
	v_exp_f32_e32 v130, v0
	v_mul_f32_e32 v0, 0xbfb8aa3b, v187
	v_exp_f32_e32 v131, v0
	s_nop 0
	v_pk_add_f32 v[130:131], v[130:131], 1.0 op_sel_hi:[1,0]
	s_nop 0
	s_nop 0
	v_rcp_f32_e32 v187, v131
	s_nop 0
	s_nop 0
	v_rcp_f32_e32 v186, v130
	s_nop 0
	v_mul_f32_e32 v0, 0xbfb8aa3b, v184
	v_exp_f32_e32 v130, v0
	v_mul_f32_e32 v0, 0xbfb8aa3b, v185
	v_exp_f32_e32 v131, v0
	s_nop 0
	v_pk_add_f32 v[130:131], v[130:131], 1.0 op_sel_hi:[1,0]
	s_nop 0
	s_nop 0
	v_rcp_f32_e32 v185, v131
	s_nop 0
	s_nop 0
	v_rcp_f32_e32 v184, v130
	s_nop 0
	v_mul_f32_e32 v0, 0xbfb8aa3b, v188
	v_exp_f32_e32 v130, v0
	v_mul_f32_e32 v0, 0xbfb8aa3b, v189
	v_exp_f32_e32 v131, v0
	s_nop 0
	v_pk_add_f32 v[130:131], v[130:131], 1.0 op_sel_hi:[1,0]
	s_nop 0
	s_nop 0
	v_rcp_f32_e32 v189, v131
	s_nop 0
	s_nop 0
	v_rcp_f32_e32 v188, v130
	s_nop 0
	s_and_b64 vcc, exec, s[44:45]
	s_cbranch_vccnz .LBB0_566
	global_load_dwordx4 v[130:133], v[134:135], off offset:512
	global_load_dwordx4 v[192:195], v[134:135], off offset:528
	s_waitcnt vmcnt(1)
	v_pk_mul_f32 v[186:187], v[186:187], v[132:133]
	v_pk_mul_f32 v[138:139], v[138:139], v[130:131]
	s_waitcnt vmcnt(0)
	v_pk_mul_f32 v[188:189], v[188:189], v[194:195]
	v_pk_mul_f32 v[184:185], v[184:185], v[192:193]

; __device__ __forceinline__ u32x4 pack8(const float (&f)[8]) { u32x4 w; w.x = pk2(f[0], f[1]); w.y = pk2(f[2], f[3]); w.z = pk2(f[4], f[5]); w.w = pk2(f[6], f[7]); return w; }
;     __device__ __forceinline__ void operator()(const pg8::f32x4 (&acc)[2][2][4][2], const pg8::Unit& u, int wr, int wc, int fr, int fq) const {
;     ...
;                         bf16_t* p = dst + (size_t)row * ldc + colb + bj * 128 + cl;
;                         if (addt) { float tv[8]; unpack8(*(const u32x4*)p, tv);
; #pragma unroll
;                             for (int e = 0; e < 8; ++e) o[e] += tv[e]; }
;                         if (ssq) {
; #pragma unroll
;                             for (int e = 0; e < 8; ++e) sacc += o[e] * o[e]; }
;                         if (mode == EM_UP) __builtin_nontemporal_store(pack8(o), (u32x4*)p); else *(u32x4*)p = pack8(o);
.LBB0_575:
	s_and_b64 vcc, exec, s[54:55]
	global_store_dwordx4 v[136:137], v[130:133], off offset:256 sc1
	s_cbranch_vccz .LBB0_580
	s_branch .LBB0_583

; __device__ __forceinline__ u32x4 pack8(const float (&f)[8]) { u32x4 w; w.x = pk2(f[0], f[1]); w.y = pk2(f[2], f[3]); w.z = pk2(f[4], f[5]); w.w = pk2(f[6], f[7]); return w; }
;     __device__ __forceinline__ void operator()(const pg8::f32x4 (&acc)[2][2][4][2], const pg8::Unit& u, int wr, int wc, int fr, int fq) const {
;     ...
;                         bf16_t* p = dst + (size_t)row * ldc + colb + bj * 128 + cl;
;                         if (addt) { float tv[8]; unpack8(*(const u32x4*)p, tv);
; #pragma unroll
;                             for (int e = 0; e < 8; ++e) o[e] += tv[e]; }
;                         if (ssq) {
; #pragma unroll
;                             for (int e = 0; e < 8; ++e) sacc += o[e] * o[e]; }
;                         if (mode == EM_UP) __builtin_nontemporal_store(pack8(o), (u32x4*)p); else *(u32x4*)p = pack8(o);
.LBB0_579:
	v_cvt_pk_bf16_f32 v130, v138, v139
	v_cvt_pk_bf16_f32 v131, v186, v187
	v_cvt_pk_bf16_f32 v132, v184, v185
	v_cvt_pk_bf16_f32 v133, v188, v189
	s_and_b64 vcc, exec, s[54:55]
	global_store_dwordx4 v[136:137], v[130:133], off offset:256 sc1
	s_cbranch_vccnz .LBB0_583
